# attention finalize: norm-weight and gate loads of each column group issued one group ahead into spare registers, counted waits (no store drain)
# speedup vs baseline: 1.0088x; 1.0015x over previous
; DI void attn_item(const Params& p, int l, int item, char* lds) {
;     ...
;   if (m == 0) {
;     float d1 = 0.f, d2 = 0.f;
;     for (int i = 0; i < 64; ++i) { d1 += p.lq1[l * 64 + i] * p.lk1[l * 64 + i]; d2 += p.lq2[l * 64 + i] * p.lk2[l * 64 + i]; }
;     const float lam_init = 0.8f - 0.6f * __expf(-0.3f * (float)l);
;     const float lam = __expf(d1) - __expf(d2) + lam_init;
;     float ss = 0.f;
; #pragma unroll
;     for (int vt = 0; vt < 4; ++vt)
; #pragma unroll
;       for (int e = 0; e < 16; ++e) {
;         const int vd = vt * 32 + (e & 3) + 8 * (e >> 2) + 4 * hh;
;         const float o2 = xb[(qh * 128 + vd) * 32 + q];
;         const float o = O[vt][e] - lam * o2; O[vt][e] = o; ss += o * o;
;       }
;     ss += __shfl_xor(ss, 32);
;     const float rstd = rsqrtf(ss * (1.0f / 128.0f) + 1e-5f) * (1.0f - lam_init);
;     const size_t row = (size_t)(qrow0 + qh * 32 + q);
;     const float* sg = p.subln_g + l * 128;
; #pragma unroll
;     for (int vt = 0; vt < 4; ++vt)
; #pragma unroll
;       for (int e4 = 0; e4 < 4; ++e4) {
;         const int vd = vt * 32 + 8 * e4 + 4 * hh;
;         const u32x2 gu = *(const u32x2*)(p.z + row * NZ + C_GA + h * 128 + vd);
;         const f32x4 gv = *(const f32x4*)(sg + vd);
.LBB0_611:
	s_add_u32 s2, s84, s0
	s_addc_u32 s3, s85, s1
	global_load_dwordx4 v[24:27], v1, s[2:3] offset:16
	global_load_dwordx4 v[28:31], v1, s[2:3]
	s_add_u32 s2, s86, s0
	s_addc_u32 s3, s87, s1
	global_load_dwordx4 v[40:43], v1, s[2:3] offset:16
	global_load_dwordx4 v[44:47], v1, s[2:3]
	s_add_u32 s2, s68, s0
	s_addc_u32 s3, s69, s1
	global_load_dwordx4 v[60:63], v1, s[2:3] offset:16
	global_load_dwordx4 v[92:95], v1, s[2:3]
	s_add_u32 s2, s70, s0
	s_addc_u32 s3, s71, s1
	global_load_dwordx4 v[96:99], v1, s[2:3] offset:16
	global_load_dwordx4 v[100:103], v1, s[2:3]
	s_add_u32 s0, s0, 32
	s_addc_u32 s1, s1, 0
	s_cmpk_eq_i32 s0, 0x100
	s_waitcnt vmcnt(6)
	v_mov_b32_e32 v79, v28
	s_waitcnt vmcnt(4)
	v_mov_b32_e32 v105, v44
	s_waitcnt vmcnt(2)
	v_mov_b32_e32 v78, v92
	v_mov_b32_e32 v28, v93
	s_waitcnt vmcnt(0)
	v_mov_b32_e32 v104, v100
	v_pk_fma_f32 v[20:21], v[78:79], v[104:105], v[20:21]
	v_mov_b32_e32 v44, v101
	v_pk_fma_f32 v[20:21], v[28:29], v[44:45], v[20:21]
	v_mov_b32_e32 v28, v94
	v_mov_b32_e32 v29, v30
	v_mov_b32_e32 v44, v102
	v_mov_b32_e32 v45, v46
	v_pk_fma_f32 v[20:21], v[28:29], v[44:45], v[20:21]
	v_mov_b32_e32 v30, v95
	v_mov_b32_e32 v46, v103
	v_pk_fma_f32 v[20:21], v[30:31], v[46:47], v[20:21]
	v_mov_b32_e32 v28, v60
	v_mov_b32_e32 v29, v24
	v_mov_b32_e32 v30, v96
	v_mov_b32_e32 v31, v40
	v_pk_fma_f32 v[20:21], v[28:29], v[30:31], v[20:21]
	v_mov_b32_e32 v24, v61
	v_mov_b32_e32 v40, v97
	v_pk_fma_f32 v[20:21], v[24:25], v[40:41], v[20:21]
	v_mov_b32_e32 v24, v62
	v_mov_b32_e32 v25, v26
	v_mov_b32_e32 v28, v98
	v_mov_b32_e32 v29, v42
	v_pk_fma_f32 v[20:21], v[24:25], v[28:29], v[20:21]
	v_mov_b32_e32 v26, v63
	v_mov_b32_e32 v42, v99
	v_pk_fma_f32 v[20:21], v[26:27], v[42:43], v[20:21]
	s_cbranch_scc0 .LBB0_611
	v_mul_f32_e32 v0, 0x3fb8aa3b, v21
	v_mul_f32_e32 v20, 0x3fb8aa3b, v20
	v_exp_f32_e32 v0, v0
	v_exp_f32_e32 v20, v20
	s_and_b32 s0, s20, 0x1ffff80
	s_lshl_b32 s0, s0, 7
	s_mov_b32 s25, s97
	v_sub_f32_e32 v0, v0, v20
	v_lshl_or_b32 v20, v169, 9, s0
	v_lshl_or_b32 v91, v163, 2, v20
	v_add_u32_e32 v20, 0x400, v91
	ds_read2_b32 v[24:25], v91 offset1:32
	ds_read2_b32 v[26:27], v91 offset0:64 offset1:96
	ds_read2_b32 v[28:29], v20 offset1:32
	ds_read2_b32 v[30:31], v20 offset0:64 offset1:96
	v_add_u32_e32 v20, 0x800, v91
	ds_read2_b32 v[40:41], v20 offset1:32
	ds_read2_b32 v[42:43], v20 offset0:64 offset1:96
	v_add_u32_e32 v20, 0xc00, v91
	ds_read2_b32 v[44:45], v20 offset1:32
	ds_read2_b32 v[46:47], v20 offset0:64 offset1:96
	v_add_u32_e32 v20, 0x1000, v91
	ds_read2_b32 v[60:61], v20 offset1:32
	ds_read2_b32 v[62:63], v20 offset0:64 offset1:96
	v_add_u32_e32 v20, 0x1400, v91
	ds_read2_b32 v[78:79], v20 offset1:32
	ds_read2_b32 v[96:97], v20 offset0:64 offset1:96
	v_add_u32_e32 v20, 0x1800, v91
	ds_read2_b32 v[98:99], v20 offset1:32
	ds_read2_b32 v[100:101], v20 offset0:64 offset1:96
	v_add_u32_e32 v20, 0x1c00, v91
	ds_read2_b32 v[102:103], v20 offset1:32
	ds_read2_b32 v[104:105], v20 offset0:64 offset1:96
	v_add_u32_e32 v20, 0x2000, v91
	ds_read2_b32 v[106:107], v20 offset1:32
	ds_read2_b32 v[108:109], v20 offset0:64 offset1:96
	v_add_u32_e32 v20, 0x2400, v91
	ds_read2_b32 v[110:111], v20 offset1:32
	ds_read2_b32 v[112:113], v20 offset0:64 offset1:96
	v_add_u32_e32 v20, 0x2800, v91
	ds_read2_b32 v[114:115], v20 offset1:32
	ds_read2_b32 v[116:117], v20 offset0:64 offset1:96
	v_add_u32_e32 v20, 0x2c00, v91
	ds_read2_b32 v[118:119], v20 offset1:32
	ds_read2_b32 v[120:121], v20 offset0:64 offset1:96
	v_add_u32_e32 v20, 0x3000, v91
	ds_read2_b32 v[122:123], v20 offset1:32
	ds_read2_b32 v[124:125], v20 offset0:64 offset1:96
	v_add_u32_e32 v20, 0x3400, v91
	v_add_u32_e32 v92, 0x3c00, v91
	ds_read2_b32 v[126:127], v20 offset1:32
	ds_read2_b32 v[128:129], v20 offset0:64 offset1:96
	ds_read2_b32 v[20:21], v92 offset1:32
	v_add_u32_e32 v91, 0x3800, v91
	ds_read2_b32 v[92:93], v92 offset0:64 offset1:96
	ds_read2_b32 v[130:131], v91 offset1:32
	ds_read2_b32 v[132:133], v91 offset0:64 offset1:96
	v_add_f32_e32 v0, v190, v0
	v_mov_b32_e32 v169, v1
	s_waitcnt lgkmcnt(3)
	v_pk_fma_f32 v[20:21], v[0:1], v[20:21], v[18:19] op_sel_hi:[0,1,1] neg_lo:[1,0,0] neg_hi:[1,0,0]
	s_waitcnt lgkmcnt(2)
	v_pk_fma_f32 v[18:19], v[0:1], v[92:93], v[22:23] op_sel_hi:[0,1,1] neg_lo:[1,0,0] neg_hi:[1,0,0]
	v_lshl_add_u64 v[22:23], v[164:165], 0, s[24:25]
	v_lshl_add_u64 v[92:93], v[22:23], 0, v[168:169]
	s_mov_b64 s[0:1], 0x1d00
	v_lshl_add_u64 v[22:23], v[92:93], 0, s[0:1]
	s_movk_i32 s0, 0x1000
	v_add_co_u32_e32 v92, vcc, s0, v92
	v_pk_fma_f32 v[86:87], v[0:1], v[24:25], v[86:87] op_sel_hi:[0,1,1] neg_lo:[1,0,0] neg_hi:[1,0,0]
	s_nop 0
	v_addc_co_u32_e32 v93, vcc, 0, v93, vcc
	v_pk_fma_f32 v[88:89], v[0:1], v[26:27], v[88:89] op_sel_hi:[0,1,1] neg_lo:[1,0,0] neg_hi:[1,0,0]
	v_pk_mul_f32 v[144:145], v[86:87], v[86:87]
	global_load_dwordx2 v[140:141], v[92:93], off offset:3328
	s_nop 0
	global_load_dwordx4 v[92:95], v162, s[22:23]
	global_load_dwordx4 v[222:225], v162, s[22:23] offset:32
	global_load_dwordx2 v[228:229], v[22:23], off offset:16
	v_pk_mul_f32 v[142:143], v[88:89], v[88:89]
	v_pk_fma_f32 v[84:85], v[0:1], v[30:31], v[84:85] op_sel_hi:[0,1,1] neg_lo:[1,0,0] neg_hi:[1,0,0]
	v_pk_fma_f32 v[80:81], v[0:1], v[28:29], v[80:81] op_sel_hi:[0,1,1] neg_lo:[1,0,0] neg_hi:[1,0,0]
	v_pk_fma_f32 v[82:83], v[0:1], v[42:43], v[82:83] op_sel_hi:[0,1,1] neg_lo:[1,0,0] neg_hi:[1,0,0]
	v_pk_fma_f32 v[70:71], v[0:1], v[40:41], v[70:71] op_sel_hi:[0,1,1] neg_lo:[1,0,0] neg_hi:[1,0,0]
	v_pk_fma_f32 v[76:77], v[0:1], v[46:47], v[76:77] op_sel_hi:[0,1,1] neg_lo:[1,0,0] neg_hi:[1,0,0]
	v_pk_fma_f32 v[156:157], v[0:1], v[44:45], v[68:69] op_sel_hi:[0,1,1] neg_lo:[1,0,0] neg_hi:[1,0,0]
; DI void attn_item(const Params& p, int l, int item, char* lds) {
;     ...
; #pragma unroll
;     for (int vt = 0; vt < 4; ++vt)
; #pragma unroll
;       for (int e = 0; e < 16; ++e) {
;         const int vd = vt * 32 + (e & 3) + 8 * (e >> 2) + 4 * hh;
;         const float o2 = xb[(qh * 128 + vd) * 32 + q];
;         const float o = O[vt][e] - lam * o2; O[vt][e] = o; ss += o * o;
;       }
;     ss += __shfl_xor(ss, 32);
	v_pk_fma_f32 v[68:69], v[0:1], v[62:63], v[74:75] op_sel_hi:[0,1,1] neg_lo:[1,0,0] neg_hi:[1,0,0]
	v_pk_fma_f32 v[66:67], v[0:1], v[60:61], v[66:67] op_sel_hi:[0,1,1] neg_lo:[1,0,0] neg_hi:[1,0,0]
	v_pk_fma_f32 v[60:61], v[0:1], v[96:97], v[72:73] op_sel_hi:[0,1,1] neg_lo:[1,0,0] neg_hi:[1,0,0]
	v_pk_fma_f32 v[62:63], v[0:1], v[78:79], v[64:65] op_sel_hi:[0,1,1] neg_lo:[1,0,0] neg_hi:[1,0,0]
	v_pk_fma_f32 v[58:59], v[0:1], v[100:101], v[58:59] op_sel_hi:[0,1,1] neg_lo:[1,0,0] neg_hi:[1,0,0]
	v_pk_fma_f32 v[52:53], v[0:1], v[98:99], v[52:53] op_sel_hi:[0,1,1] neg_lo:[1,0,0] neg_hi:[1,0,0]
	v_pk_fma_f32 v[44:45], v[0:1], v[104:105], v[56:57] op_sel_hi:[0,1,1] neg_lo:[1,0,0] neg_hi:[1,0,0]
	v_pk_fma_f32 v[46:47], v[0:1], v[102:103], v[50:51] op_sel_hi:[0,1,1] neg_lo:[1,0,0] neg_hi:[1,0,0]
	v_pk_fma_f32 v[40:41], v[0:1], v[108:109], v[54:55] op_sel_hi:[0,1,1] neg_lo:[1,0,0] neg_hi:[1,0,0]
	v_pk_fma_f32 v[42:43], v[0:1], v[106:107], v[48:49] op_sel_hi:[0,1,1] neg_lo:[1,0,0] neg_hi:[1,0,0]
	v_pk_fma_f32 v[38:39], v[0:1], v[112:113], v[38:39] op_sel_hi:[0,1,1] neg_lo:[1,0,0] neg_hi:[1,0,0]
	v_pk_fma_f32 v[32:33], v[0:1], v[110:111], v[32:33] op_sel_hi:[0,1,1] neg_lo:[1,0,0] neg_hi:[1,0,0]
	v_pk_fma_f32 v[28:29], v[0:1], v[116:117], v[36:37] op_sel_hi:[0,1,1] neg_lo:[1,0,0] neg_hi:[1,0,0]
	v_pk_fma_f32 v[30:31], v[0:1], v[114:115], v[12:13] op_sel_hi:[0,1,1] neg_lo:[1,0,0] neg_hi:[1,0,0]
	v_pk_fma_f32 v[24:25], v[0:1], v[120:121], v[34:35] op_sel_hi:[0,1,1] neg_lo:[1,0,0] neg_hi:[1,0,0]
	v_pk_fma_f32 v[26:27], v[0:1], v[118:119], v[8:9] op_sel_hi:[0,1,1] neg_lo:[1,0,0] neg_hi:[1,0,0]
	v_pk_fma_f32 v[12:13], v[0:1], v[124:125], v[16:17] op_sel_hi:[0,1,1] neg_lo:[1,0,0] neg_hi:[1,0,0]
	v_pk_fma_f32 v[16:17], v[0:1], v[122:123], v[6:7] op_sel_hi:[0,1,1] neg_lo:[1,0,0] neg_hi:[1,0,0]
	v_pk_fma_f32 v[6:7], v[0:1], v[128:129], v[14:15] op_sel_hi:[0,1,1] neg_lo:[1,0,0] neg_hi:[1,0,0]
	v_pk_fma_f32 v[8:9], v[0:1], v[126:127], v[4:5] op_sel_hi:[0,1,1] neg_lo:[1,0,0] neg_hi:[1,0,0]
	s_waitcnt lgkmcnt(0)
	v_pk_fma_f32 v[4:5], v[0:1], v[132:133], v[10:11] op_sel_hi:[0,1,1] neg_lo:[1,0,0] neg_hi:[1,0,0]
	v_pk_fma_f32 v[2:3], v[0:1], v[130:131], v[2:3] op_sel_hi:[0,1,1] neg_lo:[1,0,0] neg_hi:[1,0,0]
	v_add_f32_e32 v0, v144, v145
	v_add_f32_e32 v0, v0, v142
	v_pk_mul_f32 v[148:149], v[80:81], v[80:81]
	v_add_f32_e32 v0, v0, v143
	v_add_f32_e32 v0, v0, v148
	v_pk_mul_f32 v[146:147], v[84:85], v[84:85]
	v_add_f32_e32 v0, v0, v149
	v_add_f32_e32 v0, v0, v146
	v_pk_mul_f32 v[152:153], v[70:71], v[70:71]
	v_add_f32_e32 v0, v0, v147
	v_add_f32_e32 v0, v0, v152
	v_pk_mul_f32 v[150:151], v[82:83], v[82:83]
	v_add_f32_e32 v0, v0, v153
	v_add_f32_e32 v0, v0, v150
	v_pk_mul_f32 v[158:159], v[156:157], v[156:157]
	v_add_f32_e32 v0, v0, v151
	v_add_f32_e32 v0, v0, v158
	v_pk_mul_f32 v[154:155], v[76:77], v[76:77]
	v_add_f32_e32 v0, v0, v159
	v_add_f32_e32 v0, v0, v154
	v_pk_mul_f32 v[164:165], v[66:67], v[66:67]
	v_add_f32_e32 v0, v0, v155
	v_add_f32_e32 v0, v0, v164
	v_pk_mul_f32 v[74:75], v[68:69], v[68:69]
	v_add_f32_e32 v0, v0, v165
	v_add_f32_e32 v0, v0, v74
	v_pk_mul_f32 v[64:65], v[62:63], v[62:63]
	v_add_f32_e32 v0, v0, v75
	v_add_f32_e32 v0, v0, v64
	v_pk_mul_f32 v[72:73], v[60:61], v[60:61]
	v_add_f32_e32 v0, v0, v65
	v_add_f32_e32 v0, v0, v72
	v_pk_mul_f32 v[96:97], v[52:53], v[52:53]
	v_add_f32_e32 v0, v0, v73
	v_add_f32_e32 v0, v0, v96
	v_pk_mul_f32 v[78:79], v[58:59], v[58:59]
	v_add_f32_e32 v0, v0, v97
	v_add_f32_e32 v0, v0, v78
	v_pk_mul_f32 v[50:51], v[46:47], v[46:47]
	v_add_f32_e32 v0, v0, v79
	v_add_f32_e32 v0, v0, v50
	v_pk_mul_f32 v[56:57], v[44:45], v[44:45]
	v_add_f32_e32 v0, v0, v51
	v_add_f32_e32 v0, v0, v56
	v_pk_mul_f32 v[48:49], v[42:43], v[42:43]
	v_add_f32_e32 v0, v0, v57
	v_add_f32_e32 v0, v0, v48
	v_pk_mul_f32 v[54:55], v[40:41], v[40:41]
	v_add_f32_e32 v0, v0, v49
	v_add_f32_e32 v0, v0, v54
	v_pk_mul_f32 v[100:101], v[32:33], v[32:33]
	v_add_f32_e32 v0, v0, v55
	v_add_f32_e32 v0, v0, v100
	v_pk_mul_f32 v[98:99], v[38:39], v[38:39]
	v_add_f32_e32 v0, v0, v101
	v_add_f32_e32 v0, v0, v98
	v_pk_mul_f32 v[102:103], v[30:31], v[30:31]
	v_add_f32_e32 v0, v0, v99
	v_add_f32_e32 v0, v0, v102
	v_pk_mul_f32 v[36:37], v[28:29], v[28:29]
	v_add_f32_e32 v0, v0, v103
	v_add_f32_e32 v0, v0, v36
	v_pk_mul_f32 v[104:105], v[26:27], v[26:27]
	v_add_f32_e32 v0, v0, v37
	v_add_f32_e32 v0, v0, v104
	v_pk_mul_f32 v[34:35], v[24:25], v[24:25]
	v_add_f32_e32 v0, v0, v105
	v_add_f32_e32 v0, v0, v34
	v_pk_mul_f32 v[108:109], v[16:17], v[16:17]
	v_add_f32_e32 v0, v0, v35
	v_add_f32_e32 v0, v0, v108
	v_pk_mul_f32 v[106:107], v[12:13], v[12:13]
	v_add_f32_e32 v0, v0, v109
	v_add_f32_e32 v0, v0, v106
	v_pk_mul_f32 v[110:111], v[8:9], v[8:9]
	v_add_f32_e32 v0, v0, v107
	v_add_f32_e32 v0, v0, v110
	v_pk_mul_f32 v[14:15], v[6:7], v[6:7]
	v_add_f32_e32 v0, v0, v111
	v_add_f32_e32 v0, v0, v14
	v_pk_mul_f32 v[112:113], v[2:3], v[2:3]
	v_add_f32_e32 v0, v0, v15
	v_add_f32_e32 v0, v0, v112
	v_pk_mul_f32 v[10:11], v[4:5], v[4:5]
	v_add_f32_e32 v0, v0, v113
	v_add_f32_e32 v0, v0, v10
	v_pk_mul_f32 v[134:135], v[20:21], v[20:21]
	v_add_f32_e32 v0, v0, v11
	v_add_f32_e32 v0, v0, v134
	v_pk_mul_f32 v[136:137], v[18:19], v[18:19]
	v_add_f32_e32 v0, v0, v135
	v_add_f32_e32 v0, v0, v136
	v_add_f32_e32 v0, v0, v137
	ds_bpermute_b32 v10, v90, v0
	s_waitcnt vmcnt(3)
	v_lshlrev_b32_e32 v14, 16, v140
	v_and_b32_e32 v15, 0xffff0000, v140
	v_lshlrev_b64 v[138:139], 10, v[166:167]
	v_lshlrev_b32_e32 v34, 16, v141
	s_waitcnt lgkmcnt(0)
; DI unsigned pk2(float a, float b) { f32x2 v = {a, b}; bfv2 r = __builtin_convertvector(v, bfv2); return __builtin_bit_cast(unsigned, r); }
; DI float bf_lo(unsigned u) { return __uint_as_float(u << 16); }
; DI float bf_hi(unsigned u) { return __uint_as_float(u & 0xffff0000u); }
; DI void attn_item(const Params& p, int l, int item, char* lds) {
;     ...
;     ss += __shfl_xor(ss, 32);
;     const float rstd = rsqrtf(ss * (1.0f / 128.0f) + 1e-5f) * (1.0f - lam_init);
;     const size_t row = (size_t)(qrow0 + qh * 32 + q);
;     const float* sg = p.subln_g + l * 128;
; #pragma unroll
;     for (int vt = 0; vt < 4; ++vt)
; #pragma unroll
;       for (int e4 = 0; e4 < 4; ++e4) {
;         const int vd = vt * 32 + 8 * e4 + 4 * hh;
;         const u32x2 gu = *(const u32x2*)(p.z + row * NZ + C_GA + h * 128 + vd);
;         const f32x4 gv = *(const f32x4*)(sg + vd);
;         const float y0 = O[vt][4 * e4 + 0] * rstd * gv[0] * bf_lo(gu[0]);
;         const float y1 = O[vt][4 * e4 + 1] * rstd * gv[1] * bf_hi(gu[0]);
;         const float y2 = O[vt][4 * e4 + 2] * rstd * gv[2] * bf_lo(gu[1]);
;         const float y3 = O[vt][4 * e4 + 3] * rstd * gv[3] * bf_hi(gu[1]);
;         u32x2 ov; ov[0] = pk2(y0, y1); ov[1] = pk2(y2, y3);
;         *(u32x2*)(p.o_a + row * 512 + h * 128 + vd) = ov;
;       }
	v_add_f32_e32 v0, v0, v10
	v_mov_b32_e32 v10, 0x3727c5ac
	v_fmamk_f32 v0, v0, 0x3c000000, v10
	v_mul_f32_e32 v10, 0x4b800000, v0
	v_cmp_gt_f32_e32 vcc, s34, v0
	v_and_b32_e32 v35, 0xffff0000, v141
	s_mov_b32 s84, s21
	v_cndmask_b32_e32 v0, v0, v10, vcc
	v_rsq_f32_e32 v0, v0
	v_lshl_add_u64 v[10:11], s[54:55], 0, v[138:139]
	v_lshl_add_u64 v[10:11], v[10:11], 0, s[24:25]
	v_lshl_add_u64 v[10:11], v[10:11], 0, v[168:169]
	v_mul_f32_e32 v36, 0x45800000, v0
	v_cndmask_b32_e32 v0, v0, v36, vcc
	v_mul_f32_e32 v0, v191, v0
	v_pk_mul_f32 v[36:37], v[86:87], v[0:1] op_sel_hi:[1,0]
	v_pk_mul_f32 v[48:49], v[80:81], v[0:1] op_sel_hi:[1,0]
	s_waitcnt vmcnt(2)
	v_pk_mul_f32 v[36:37], v[92:93], v[36:37]
	v_pk_mul_f32 v[50:51], v[82:83], v[0:1] op_sel_hi:[1,0]
	v_pk_mul_f32 v[14:15], v[36:37], v[14:15]
	v_pk_mul_f32 v[36:37], v[88:89], v[0:1] op_sel_hi:[1,0]
	v_cvt_pk_bf16_f32 v14, v14, v15
	v_pk_mul_f32 v[36:37], v[94:95], v[36:37]
	v_pk_mul_f32 v[46:47], v[46:47], v[0:1] op_sel_hi:[1,0]
	v_pk_mul_f32 v[34:35], v[36:37], v[34:35]
	v_pk_mul_f32 v[44:45], v[44:45], v[0:1] op_sel_hi:[1,0]
	v_cvt_pk_bf16_f32 v15, v34, v35
	global_store_dwordx2 v[10:11], v[14:15], off
	global_load_dwordx4 v[214:217], v162, s[22:23] offset:64
	s_nop 0
	global_load_dwordx2 v[226:227], v[22:23], off offset:32
	v_pk_mul_f32 v[42:43], v[42:43], v[0:1] op_sel_hi:[1,0]
	v_pk_mul_f32 v[40:41], v[40:41], v[0:1] op_sel_hi:[1,0]
	v_pk_mul_f32 v[32:33], v[32:33], v[0:1] op_sel_hi:[1,0]
	v_pk_mul_f32 v[38:39], v[38:39], v[0:1] op_sel_hi:[1,0]
	v_pk_mul_f32 v[30:31], v[30:31], v[0:1] op_sel_hi:[1,0]
	v_pk_mul_f32 v[28:29], v[28:29], v[0:1] op_sel_hi:[1,0]
	v_pk_mul_f32 v[26:27], v[26:27], v[0:1] op_sel_hi:[1,0]
	v_pk_mul_f32 v[24:25], v[24:25], v[0:1] op_sel_hi:[1,0]
	v_pk_mul_f32 v[16:17], v[16:17], v[0:1] op_sel_hi:[1,0]
	v_pk_mul_f32 v[12:13], v[12:13], v[0:1] op_sel_hi:[1,0]
	v_pk_mul_f32 v[8:9], v[8:9], v[0:1] op_sel_hi:[1,0]
	v_pk_mul_f32 v[6:7], v[6:7], v[0:1] op_sel_hi:[1,0]
	v_pk_mul_f32 v[2:3], v[2:3], v[0:1] op_sel_hi:[1,0]
	v_pk_mul_f32 v[4:5], v[4:5], v[0:1] op_sel_hi:[1,0]
	s_mov_b32 s85, s26
	s_mov_b32 s86, s27
	s_mov_b32 s87, s30
	s_waitcnt vmcnt(4)
	v_mov_b32_e32 v34, v222
	v_mov_b32_e32 v35, v223
	v_mov_b32_e32 v36, v224
	v_mov_b32_e32 v37, v225
	v_pk_mul_f32 v[34:35], v[34:35], v[48:49]
	s_waitcnt vmcnt(3)
	v_mov_b32_e32 v14, v228
	v_mov_b32_e32 v15, v229
	v_lshlrev_b32_e32 v48, 16, v14
	v_and_b32_e32 v49, 0xffff0000, v14
	v_pk_mul_f32 v[34:35], v[34:35], v[48:49]
	v_pk_mul_f32 v[48:49], v[84:85], v[0:1] op_sel_hi:[1,0]
	v_lshlrev_b32_e32 v14, 16, v15
	v_pk_mul_f32 v[36:37], v[36:37], v[48:49]
	v_and_b32_e32 v15, 0xffff0000, v15
	v_pk_mul_f32 v[14:15], v[36:37], v[14:15]
	v_cvt_pk_bf16_f32 v34, v34, v35
	v_cvt_pk_bf16_f32 v35, v14, v15
	global_store_dwordx2 v[10:11], v[34:35], off offset:16
	global_load_dwordx4 v[222:225], v162, s[22:23] offset:96
	s_nop 0
	global_load_dwordx2 v[228:229], v[22:23], off offset:48
	v_pk_mul_f32 v[48:49], v[70:71], v[0:1] op_sel_hi:[1,0]
	s_waitcnt vmcnt(4)
	v_mov_b32_e32 v34, v214
	v_mov_b32_e32 v35, v215
	v_mov_b32_e32 v36, v216
	v_mov_b32_e32 v37, v217
	v_pk_mul_f32 v[36:37], v[36:37], v[50:51]
	v_pk_mul_f32 v[34:35], v[34:35], v[48:49]
	s_waitcnt vmcnt(3)
	v_mov_b32_e32 v14, v226
	v_mov_b32_e32 v15, v227
	v_lshlrev_b32_e32 v48, 16, v14
	v_and_b32_e32 v49, 0xffff0000, v14
	v_lshlrev_b32_e32 v14, 16, v15
	v_and_b32_e32 v15, 0xffff0000, v15
	v_pk_mul_f32 v[34:35], v[34:35], v[48:49]
	v_pk_mul_f32 v[14:15], v[36:37], v[14:15]
	v_cvt_pk_bf16_f32 v34, v34, v35
	v_cvt_pk_bf16_f32 v35, v14, v15
	global_store_dwordx2 v[10:11], v[34:35], off offset:32
	global_load_dwordx4 v[214:217], v162, s[22:23] offset:128
	s_nop 0
	global_load_dwordx2 v[226:227], v[22:23], off offset:64
	v_pk_mul_f32 v[48:49], v[156:157], v[0:1] op_sel_hi:[1,0]
	v_pk_mul_f32 v[50:51], v[76:77], v[0:1] op_sel_hi:[1,0]
	s_waitcnt vmcnt(4)
	v_mov_b32_e32 v34, v222
	v_mov_b32_e32 v35, v223
	v_mov_b32_e32 v36, v224
	v_mov_b32_e32 v37, v225
	v_pk_mul_f32 v[34:35], v[34:35], v[48:49]
	s_waitcnt vmcnt(3)
	v_mov_b32_e32 v14, v228
	v_mov_b32_e32 v15, v229
	v_lshlrev_b32_e32 v48, 16, v14
	v_and_b32_e32 v49, 0xffff0000, v14
	v_pk_mul_f32 v[36:37], v[36:37], v[50:51]
	v_lshlrev_b32_e32 v14, 16, v15
	v_and_b32_e32 v15, 0xffff0000, v15
	v_pk_mul_f32 v[34:35], v[34:35], v[48:49]
	v_pk_mul_f32 v[14:15], v[36:37], v[14:15]
	v_cvt_pk_bf16_f32 v34, v34, v35
	v_cvt_pk_bf16_f32 v35, v14, v15
	global_store_dwordx2 v[10:11], v[34:35], off offset:48
	global_load_dwordx4 v[222:225], v162, s[22:23] offset:160
	s_nop 0
	global_load_dwordx2 v[228:229], v[22:23], off offset:80
	v_pk_mul_f32 v[48:49], v[66:67], v[0:1] op_sel_hi:[1,0]
	v_pk_mul_f32 v[50:51], v[68:69], v[0:1] op_sel_hi:[1,0]
	s_waitcnt vmcnt(4)
	v_mov_b32_e32 v34, v214
	v_mov_b32_e32 v35, v215
	v_mov_b32_e32 v36, v216
	v_mov_b32_e32 v37, v217
	v_pk_mul_f32 v[34:35], v[48:49], v[34:35]
	s_waitcnt vmcnt(3)
	v_mov_b32_e32 v14, v226
	v_mov_b32_e32 v15, v227
	v_lshlrev_b32_e32 v48, 16, v14
	v_and_b32_e32 v49, 0xffff0000, v14
	v_pk_mul_f32 v[36:37], v[50:51], v[36:37]
	v_lshlrev_b32_e32 v14, 16, v15
	v_and_b32_e32 v15, 0xffff0000, v15
	v_pk_mul_f32 v[34:35], v[34:35], v[48:49]
	v_pk_mul_f32 v[14:15], v[36:37], v[14:15]
	v_cvt_pk_bf16_f32 v34, v34, v35
	v_cvt_pk_bf16_f32 v35, v14, v15
	global_store_dwordx2 v[10:11], v[34:35], off offset:64
	global_load_dwordx4 v[214:217], v162, s[22:23] offset:192
	s_nop 0
	global_load_dwordx2 v[226:227], v[22:23], off offset:96
	v_pk_mul_f32 v[48:49], v[62:63], v[0:1] op_sel_hi:[1,0]
	v_pk_mul_f32 v[50:51], v[60:61], v[0:1] op_sel_hi:[1,0]
	s_waitcnt vmcnt(4)
; DI unsigned pk2(float a, float b) { f32x2 v = {a, b}; bfv2 r = __builtin_convertvector(v, bfv2); return __builtin_bit_cast(unsigned, r); }
; DI float bf_lo(unsigned u) { return __uint_as_float(u << 16); }
; DI float bf_hi(unsigned u) { return __uint_as_float(u & 0xffff0000u); }
; DI void attn_item(const Params& p, int l, int item, char* lds) {
;     ...
; #pragma unroll
;     for (int vt = 0; vt < 4; ++vt)
; #pragma unroll
;       for (int e4 = 0; e4 < 4; ++e4) {
;         const int vd = vt * 32 + 8 * e4 + 4 * hh;
;         const u32x2 gu = *(const u32x2*)(p.z + row * NZ + C_GA + h * 128 + vd);
;         const f32x4 gv = *(const f32x4*)(sg + vd);
;         const float y0 = O[vt][4 * e4 + 0] * rstd * gv[0] * bf_lo(gu[0]);
;         const float y1 = O[vt][4 * e4 + 1] * rstd * gv[1] * bf_hi(gu[0]);
;         const float y2 = O[vt][4 * e4 + 2] * rstd * gv[2] * bf_lo(gu[1]);
;         const float y3 = O[vt][4 * e4 + 3] * rstd * gv[3] * bf_hi(gu[1]);
;         u32x2 ov; ov[0] = pk2(y0, y1); ov[1] = pk2(y2, y3);
;         *(u32x2*)(p.o_a + row * 512 + h * 128 + vd) = ov;
;       }
	v_mov_b32_e32 v34, v222
	v_mov_b32_e32 v35, v223
	v_mov_b32_e32 v36, v224
	v_mov_b32_e32 v37, v225
	v_pk_mul_f32 v[34:35], v[48:49], v[34:35]
	s_waitcnt vmcnt(3)
	v_mov_b32_e32 v14, v228
	v_mov_b32_e32 v15, v229
	v_lshlrev_b32_e32 v48, 16, v14
	v_and_b32_e32 v49, 0xffff0000, v14
	v_pk_mul_f32 v[36:37], v[50:51], v[36:37]
	v_lshlrev_b32_e32 v14, 16, v15
	v_and_b32_e32 v15, 0xffff0000, v15
	v_pk_mul_f32 v[34:35], v[34:35], v[48:49]
	v_pk_mul_f32 v[14:15], v[36:37], v[14:15]
	v_cvt_pk_bf16_f32 v34, v34, v35
	v_cvt_pk_bf16_f32 v35, v14, v15
	global_store_dwordx2 v[10:11], v[34:35], off offset:80
	global_load_dwordx4 v[222:225], v162, s[22:23] offset:224
	s_nop 0
	global_load_dwordx2 v[228:229], v[22:23], off offset:112
	v_pk_mul_f32 v[48:49], v[52:53], v[0:1] op_sel_hi:[1,0]
	v_pk_mul_f32 v[50:51], v[58:59], v[0:1] op_sel_hi:[1,0]
	s_waitcnt vmcnt(4)
	v_mov_b32_e32 v34, v214
	v_mov_b32_e32 v35, v215
	v_mov_b32_e32 v36, v216
	v_mov_b32_e32 v37, v217
	v_pk_mul_f32 v[34:35], v[48:49], v[34:35]
	s_waitcnt vmcnt(3)
	v_mov_b32_e32 v14, v226
	v_mov_b32_e32 v15, v227
	v_lshlrev_b32_e32 v48, 16, v14
	v_and_b32_e32 v49, 0xffff0000, v14
	v_pk_mul_f32 v[36:37], v[50:51], v[36:37]
	v_lshlrev_b32_e32 v14, 16, v15
	v_and_b32_e32 v15, 0xffff0000, v15
	v_pk_mul_f32 v[34:35], v[34:35], v[48:49]
	v_pk_mul_f32 v[14:15], v[36:37], v[14:15]
	v_cvt_pk_bf16_f32 v34, v34, v35
	v_cvt_pk_bf16_f32 v35, v14, v15
	global_store_dwordx2 v[10:11], v[34:35], off offset:96
	global_load_dwordx4 v[214:217], v162, s[22:23] offset:256
	s_nop 0
	global_load_dwordx2 v[226:227], v[22:23], off offset:128
	s_waitcnt vmcnt(4)
	v_mov_b32_e32 v34, v222
	v_mov_b32_e32 v35, v223
	v_mov_b32_e32 v36, v224
	v_mov_b32_e32 v37, v225
	v_pk_mul_f32 v[34:35], v[46:47], v[34:35]
	s_waitcnt vmcnt(3)
	v_mov_b32_e32 v14, v228
	v_mov_b32_e32 v15, v229
	v_lshlrev_b32_e32 v46, 16, v14
	v_and_b32_e32 v47, 0xffff0000, v14
	v_pk_mul_f32 v[36:37], v[44:45], v[36:37]
	v_lshlrev_b32_e32 v14, 16, v15
	v_and_b32_e32 v15, 0xffff0000, v15
	v_pk_mul_f32 v[34:35], v[34:35], v[46:47]
	v_pk_mul_f32 v[14:15], v[36:37], v[14:15]
	v_cvt_pk_bf16_f32 v34, v34, v35
	v_cvt_pk_bf16_f32 v35, v14, v15
	global_store_dwordx2 v[10:11], v[34:35], off offset:112
	global_load_dwordx4 v[222:225], v162, s[22:23] offset:288
	s_nop 0
	global_load_dwordx2 v[228:229], v[22:23], off offset:144
	s_waitcnt vmcnt(4)
	v_mov_b32_e32 v34, v214
	v_mov_b32_e32 v35, v215
	v_mov_b32_e32 v36, v216
	v_mov_b32_e32 v37, v217
	v_pk_mul_f32 v[34:35], v[42:43], v[34:35]
	s_waitcnt vmcnt(3)
	v_mov_b32_e32 v14, v226
	v_mov_b32_e32 v15, v227
	v_lshlrev_b32_e32 v42, 16, v14
	v_and_b32_e32 v43, 0xffff0000, v14
	v_pk_mul_f32 v[36:37], v[40:41], v[36:37]
	v_lshlrev_b32_e32 v14, 16, v15
	v_and_b32_e32 v15, 0xffff0000, v15
	v_pk_mul_f32 v[34:35], v[34:35], v[42:43]
	v_pk_mul_f32 v[14:15], v[36:37], v[14:15]
	v_cvt_pk_bf16_f32 v34, v34, v35
	v_cvt_pk_bf16_f32 v35, v14, v15
	global_store_dwordx2 v[10:11], v[34:35], off offset:128
	global_load_dwordx4 v[214:217], v162, s[22:23] offset:320
	s_nop 0
	global_load_dwordx2 v[226:227], v[22:23], off offset:160
	s_waitcnt vmcnt(4)
	v_mov_b32_e32 v34, v222
	v_mov_b32_e32 v35, v223
	v_mov_b32_e32 v36, v224
	v_mov_b32_e32 v37, v225
	v_pk_mul_f32 v[32:33], v[32:33], v[34:35]
	s_waitcnt vmcnt(3)
	v_mov_b32_e32 v14, v228
	v_mov_b32_e32 v15, v229
	v_lshlrev_b32_e32 v34, 16, v14
	v_and_b32_e32 v35, 0xffff0000, v14
	v_pk_mul_f32 v[36:37], v[38:39], v[36:37]
	v_lshlrev_b32_e32 v14, 16, v15
	v_and_b32_e32 v15, 0xffff0000, v15
	v_pk_mul_f32 v[32:33], v[32:33], v[34:35]
	v_pk_mul_f32 v[14:15], v[36:37], v[14:15]
	v_cvt_pk_bf16_f32 v32, v32, v33
	v_cvt_pk_bf16_f32 v33, v14, v15
	global_store_dwordx2 v[10:11], v[32:33], off offset:144
	global_load_dwordx4 v[222:225], v162, s[22:23] offset:352
	s_nop 0
	global_load_dwordx2 v[228:229], v[22:23], off offset:176
	s_waitcnt vmcnt(4)
	v_mov_b32_e32 v32, v214
	v_mov_b32_e32 v33, v215
	v_mov_b32_e32 v34, v216
	v_mov_b32_e32 v35, v217
	v_pk_mul_f32 v[30:31], v[30:31], v[32:33]
	s_waitcnt vmcnt(3)
; DI unsigned pk2(float a, float b) { f32x2 v = {a, b}; bfv2 r = __builtin_convertvector(v, bfv2); return __builtin_bit_cast(unsigned, r); }
; DI float bf_lo(unsigned u) { return __uint_as_float(u << 16); }
; DI float bf_hi(unsigned u) { return __uint_as_float(u & 0xffff0000u); }
; DI void attn_item(const Params& p, int l, int item, char* lds) {
;     ...
; #pragma unroll
;     for (int vt = 0; vt < 4; ++vt)
; #pragma unroll
;       for (int e4 = 0; e4 < 4; ++e4) {
;         const int vd = vt * 32 + 8 * e4 + 4 * hh;
;         const u32x2 gu = *(const u32x2*)(p.z + row * NZ + C_GA + h * 128 + vd);
;         const f32x4 gv = *(const f32x4*)(sg + vd);
;         const float y0 = O[vt][4 * e4 + 0] * rstd * gv[0] * bf_lo(gu[0]);
;         const float y1 = O[vt][4 * e4 + 1] * rstd * gv[1] * bf_hi(gu[0]);
;         const float y2 = O[vt][4 * e4 + 2] * rstd * gv[2] * bf_lo(gu[1]);
;         const float y3 = O[vt][4 * e4 + 3] * rstd * gv[3] * bf_hi(gu[1]);
;         u32x2 ov; ov[0] = pk2(y0, y1); ov[1] = pk2(y2, y3);
;         *(u32x2*)(p.o_a + row * 512 + h * 128 + vd) = ov;
;       }
	v_mov_b32_e32 v14, v226
	v_mov_b32_e32 v15, v227
	v_lshlrev_b32_e32 v32, 16, v14
	v_and_b32_e32 v33, 0xffff0000, v14
	v_pk_mul_f32 v[28:29], v[28:29], v[34:35]
	v_lshlrev_b32_e32 v14, 16, v15
	v_and_b32_e32 v15, 0xffff0000, v15
	v_pk_mul_f32 v[30:31], v[30:31], v[32:33]
	v_pk_mul_f32 v[14:15], v[28:29], v[14:15]
	v_cvt_pk_bf16_f32 v28, v30, v31
	v_cvt_pk_bf16_f32 v29, v14, v15
	global_store_dwordx2 v[10:11], v[28:29], off offset:160
	global_load_dwordx4 v[214:217], v162, s[22:23] offset:384
	s_nop 0
	global_load_dwordx2 v[226:227], v[22:23], off offset:192
	s_waitcnt vmcnt(4)
	v_mov_b32_e32 v28, v222
	v_mov_b32_e32 v29, v223
	v_mov_b32_e32 v30, v224
	v_mov_b32_e32 v31, v225
	v_pk_mul_f32 v[26:27], v[26:27], v[28:29]
	s_waitcnt vmcnt(3)
	v_mov_b32_e32 v14, v228
	v_mov_b32_e32 v15, v229
	v_lshlrev_b32_e32 v28, 16, v14
	v_and_b32_e32 v29, 0xffff0000, v14
	v_pk_mul_f32 v[24:25], v[24:25], v[30:31]
	v_lshlrev_b32_e32 v14, 16, v15
	v_and_b32_e32 v15, 0xffff0000, v15
	v_pk_mul_f32 v[26:27], v[26:27], v[28:29]
	v_pk_mul_f32 v[14:15], v[24:25], v[14:15]
	v_cvt_pk_bf16_f32 v24, v26, v27
	v_cvt_pk_bf16_f32 v25, v14, v15
	global_store_dwordx2 v[10:11], v[24:25], off offset:176
	global_load_dwordx4 v[222:225], v162, s[22:23] offset:416
	s_nop 0
	global_load_dwordx2 v[228:229], v[22:23], off offset:208
	s_waitcnt vmcnt(4)
	v_mov_b32_e32 v24, v214
	v_mov_b32_e32 v25, v215
	v_mov_b32_e32 v26, v216
	v_mov_b32_e32 v27, v217
	v_pk_mul_f32 v[16:17], v[16:17], v[24:25]
	s_waitcnt vmcnt(3)
	v_mov_b32_e32 v14, v226
	v_mov_b32_e32 v15, v227
	v_lshlrev_b32_e32 v24, 16, v14
	v_and_b32_e32 v25, 0xffff0000, v14
	v_pk_mul_f32 v[12:13], v[12:13], v[26:27]
	v_lshlrev_b32_e32 v14, 16, v15
	v_and_b32_e32 v15, 0xffff0000, v15
	v_pk_mul_f32 v[16:17], v[16:17], v[24:25]
	v_pk_mul_f32 v[12:13], v[12:13], v[14:15]
	v_cvt_pk_bf16_f32 v14, v16, v17
	v_cvt_pk_bf16_f32 v15, v12, v13
	global_store_dwordx2 v[10:11], v[14:15], off offset:192
	global_load_dwordx4 v[214:217], v162, s[22:23] offset:448
	s_nop 0
	global_load_dwordx2 v[226:227], v[22:23], off offset:224
	s_waitcnt vmcnt(4)
	v_mov_b32_e32 v12, v222
	v_mov_b32_e32 v13, v223
	v_mov_b32_e32 v14, v224
	v_mov_b32_e32 v15, v225
	v_pk_mul_f32 v[8:9], v[8:9], v[12:13]
	s_waitcnt vmcnt(3)
	v_mov_b32_e32 v16, v228
	v_mov_b32_e32 v17, v229
	v_lshlrev_b32_e32 v12, 16, v16
	v_and_b32_e32 v13, 0xffff0000, v16
	v_pk_mul_f32 v[6:7], v[6:7], v[14:15]
	v_lshlrev_b32_e32 v14, 16, v17
	v_and_b32_e32 v15, 0xffff0000, v17
	v_pk_mul_f32 v[8:9], v[8:9], v[12:13]
	v_pk_mul_f32 v[6:7], v[6:7], v[14:15]
	v_cvt_pk_bf16_f32 v8, v8, v9
	v_cvt_pk_bf16_f32 v9, v6, v7
	global_store_dwordx2 v[10:11], v[8:9], off offset:208
	global_load_dwordx4 v[222:225], v162, s[22:23] offset:480
	s_nop 0
	global_load_dwordx2 v[228:229], v[22:23], off offset:240
	s_waitcnt vmcnt(4)
	v_mov_b32_e32 v6, v214
	v_mov_b32_e32 v7, v215
	v_mov_b32_e32 v8, v216
	v_mov_b32_e32 v9, v217
	v_pk_mul_f32 v[2:3], v[2:3], v[6:7]
	s_waitcnt vmcnt(3)
	v_mov_b32_e32 v12, v226
	v_mov_b32_e32 v13, v227
	v_lshlrev_b32_e32 v6, 16, v12
	v_and_b32_e32 v7, 0xffff0000, v12
	v_pk_mul_f32 v[4:5], v[4:5], v[8:9]
	v_lshlrev_b32_e32 v8, 16, v13
	v_and_b32_e32 v9, 0xffff0000, v13
	v_pk_mul_f32 v[2:3], v[2:3], v[6:7]
	v_pk_mul_f32 v[4:5], v[4:5], v[8:9]
	v_cvt_pk_bf16_f32 v2, v2, v3
	v_cvt_pk_bf16_f32 v3, v4, v5
	global_store_dwordx2 v[10:11], v[2:3], off offset:224
	s_nop 0
	v_pk_mul_f32 v[8:9], v[20:21], v[0:1] op_sel_hi:[1,0]
	v_pk_mul_f32 v[12:13], v[18:19], v[0:1] op_sel_hi:[1,0]
	s_waitcnt vmcnt(2)
	v_mov_b32_e32 v2, v222
	v_mov_b32_e32 v3, v223
	v_mov_b32_e32 v4, v224
	v_mov_b32_e32 v5, v225
	v_pk_mul_f32 v[2:3], v[8:9], v[2:3]
	s_waitcnt vmcnt(1)
	v_mov_b32_e32 v6, v228
	v_mov_b32_e32 v7, v229
	v_lshlrev_b32_e32 v8, 16, v6
	v_and_b32_e32 v9, 0xffff0000, v6
	v_pk_mul_f32 v[4:5], v[12:13], v[4:5]
	v_lshlrev_b32_e32 v6, 16, v7
	v_and_b32_e32 v7, 0xffff0000, v7
	v_pk_mul_f32 v[2:3], v[2:3], v[8:9]
	v_pk_mul_f32 v[4:5], v[4:5], v[6:7]
	v_cvt_pk_bf16_f32 v2, v2, v3
	v_cvt_pk_bf16_f32 v3, v4, v5
	global_store_dwordx2 v[10:11], v[2:3], off offset:240
	s_branch .LBB0_571
